# panel-group barrier in flag form: each of the 4 workgroups stores its seam ordinal in its own word of a 16-byte record and polls the record (no atomics)
# speedup vs baseline: 1.0224x; 1.0051x over previous
; __global__ void __launch_bounds__(NWAVES * 64, 2) mk_fwd(Args args) {
;     ...
;     const int tid = threadIdx.x, wave = __builtin_amdgcn_readfirstlane(tid >> 6);
;     ...
;     const int G = gridDim.x; int vcu; { const int bx = blockIdx.x; vcu = (G % 8 == 0) ? (bx % 8) * (G / 8) + bx / 8 : bx; }
_Z6mk_fwd4Args:
	s_mov_b32 s101, 0
	s_load_dword s96, s[0:1], 0x90
	s_load_dwordx2 s[4:5], s[0:1], 0x80
	v_readfirstlane_b32 s33, v0
	s_waitcnt lgkmcnt(0)
	v_writelane_b32 v242, s4, 0
	s_nop 1
	v_writelane_b32 v242, s5, 1
	s_add_u32 s4, s0, 0x90
	s_addc_u32 s5, s1, 0
	v_writelane_b32 v242, s4, 2
	s_nop 1
	v_writelane_b32 v242, s5, 3
	s_and_b32 s5, s96, 7
	s_mov_b32 s4, 0
	s_cmp_lg_u32 s5, 0
	v_writelane_b32 v242, s2, 4
	v_writelane_b32 v242, s2, 5
	s_cbranch_scc1 .LBB0_2
	v_readlane_b32 s2, v242, 4
	s_ashr_i32 s6, s2, 31
	s_lshr_b32 s6, s6, 29
	s_add_i32 s6, s2, s6
	s_and_b32 s7, s6, -8
	s_ashr_i32 s5, s96, 3
	s_sub_i32 s7, s2, s7
	s_mul_i32 s5, s5, s7
	s_ashr_i32 s6, s6, 3
	s_add_i32 s5, s5, s6
	v_writelane_b32 v242, s5, 5

; __device__ __forceinline__ unsigned xb_ld(unsigned* p)              { return __hip_atomic_load(p, __ATOMIC_RELAXED, __HIP_MEMORY_SCOPE_AGENT); }
; __device__ __forceinline__ unsigned xb_add(unsigned* p, unsigned v) { return __hip_atomic_fetch_add(p, v, __ATOMIC_RELAXED, __HIP_MEMORY_SCOPE_AGENT); }
; #define XB_SPIN(cond, bar) do { unsigned _sp = 0; while (cond) { __builtin_amdgcn_s_sleep(1); \
;     if ((++_sp & 255u) == 0u) { if (xb_ld(&(bar)[XB_TMO])) break; if (_sp > XB_SPIN_CAP) { atomicAdd(&(bar)[XB_TMO], 1u); break; } } } } while (0)
; __device__ __forceinline__ void xcc_local_barrier(unsigned* bar2, unsigned x, unsigned nloc, unsigned* tmobar) {
;     asm volatile("s_waitcnt vmcnt(0)" ::: "memory");
;     __syncthreads();
;     if (threadIdx.x == 0) {
;         const unsigned old = xb_add(&bar2[XB_XSUB(x)], 1u);
;         const unsigned gen = old / nloc;
;         if (old + 1u == (gen + 1u) * nloc) (void)xb_add(&bar2[XB_XGEN(x)], 1u);
;         else XB_SPIN(xb_ld(&bar2[XB_XGEN(x)]) == gen, tmobar);
;         __builtin_amdgcn_fence(__ATOMIC_ACQUIRE, "agent");
;         asm volatile("s_waitcnt vmcnt(0)" ::: "memory");
;     }
;     __syncthreads();
.LBB0_478:
	s_and_b64 vcc, exec, s[38:39]
	s_cbranch_vccz .LBB0_498
	v_readlane_b32 s6, v238, 25
	s_nop 1
	v_mov_b32_e32 v2, s6
	ds_read_b32 v2, v2
	s_waitcnt vmcnt(0)
	v_readlane_b32 s6, v242, 38
	v_readlane_b32 s7, v242, 39
	s_waitcnt vmcnt(0) lgkmcnt(0)
	s_barrier
	s_and_saveexec_b64 s[38:39], s[6:7]
	s_cbranch_execz .LBB0_497
	s_add_i32 s101, s101, 1
	v_readlane_b32 s6, v239, 63
	v_readlane_b32 s7, v241, 0
	v_readlane_b32 s98, v242, 4
	v_mov_b32_e32 v3, s101
	s_nop 3
	s_lshr_b32 s98, s98, 6
	s_lshl_b32 s98, s98, 2
	v_mov_b32_e32 v4, s98
	global_store_dword v4, v3, s[6:7] offset:128 sc1
	buffer_inv sc1
	s_mov_b32 s100, 0
.Lgrp_poll_0:
	global_load_dwordx4 v[4:7], v66, s[6:7] offset:128 sc1
	s_waitcnt vmcnt(0)
	v_min_u32_e32 v4, v4, v5
	v_min3_u32 v4, v4, v6, v7
	s_nop 0
	v_readfirstlane_b32 s98, v4
	s_nop 3
	s_cmp_ge_u32 s98, s101
	s_cbranch_scc1 .Lgrp_done_0
	s_sleep 1
	s_add_i32 s100, s100, 1
	s_cmp_lt_u32 s100, 0x10000
	s_cbranch_scc1 .Lgrp_poll_0

; __device__ __forceinline__ unsigned xb_ld(unsigned* p)              { return __hip_atomic_load(p, __ATOMIC_RELAXED, __HIP_MEMORY_SCOPE_AGENT); }
; __device__ __forceinline__ unsigned xb_add(unsigned* p, unsigned v) { return __hip_atomic_fetch_add(p, v, __ATOMIC_RELAXED, __HIP_MEMORY_SCOPE_AGENT); }
; #define XB_SPIN(cond, bar) do { unsigned _sp = 0; while (cond) { __builtin_amdgcn_s_sleep(1); \
;     if ((++_sp & 255u) == 0u) { if (xb_ld(&(bar)[XB_TMO])) break; if (_sp > XB_SPIN_CAP) { atomicAdd(&(bar)[XB_TMO], 1u); break; } } } } while (0)
; __device__ __forceinline__ void xcc_local_barrier(unsigned* bar2, unsigned x, unsigned nloc, unsigned* tmobar) {
;     asm volatile("s_waitcnt vmcnt(0)" ::: "memory");
;     __syncthreads();
;     if (threadIdx.x == 0) {
;         const unsigned old = xb_add(&bar2[XB_XSUB(x)], 1u);
;         const unsigned gen = old / nloc;
;         if (old + 1u == (gen + 1u) * nloc) (void)xb_add(&bar2[XB_XGEN(x)], 1u);
;         else XB_SPIN(xb_ld(&bar2[XB_XGEN(x)]) == gen, tmobar);
.LBB0_612:
	s_and_b64 vcc, exec, s[40:41]
	s_cbranch_vccz .LBB0_632
	v_readlane_b32 s6, v238, 25
	s_nop 1
	v_mov_b32_e32 v2, s6
	ds_read_b32 v2, v2
	s_waitcnt vmcnt(0)
	v_readlane_b32 s6, v242, 38
	v_readlane_b32 s7, v242, 39
	s_waitcnt vmcnt(0) lgkmcnt(0)
	s_barrier
	s_and_saveexec_b64 s[40:41], s[6:7]
	s_cbranch_execz .LBB0_631
	s_add_i32 s101, s101, 1
	v_readlane_b32 s6, v239, 63
	v_readlane_b32 s7, v241, 0
	v_readlane_b32 s98, v242, 4
	v_mov_b32_e32 v3, s101
	s_nop 3
	s_lshr_b32 s98, s98, 6
	s_lshl_b32 s98, s98, 2
	v_mov_b32_e32 v4, s98
	global_store_dword v4, v3, s[6:7] offset:128 sc1
	buffer_inv sc1
	s_mov_b32 s100, 0

; __device__ __forceinline__ unsigned xb_ld(unsigned* p)              { return __hip_atomic_load(p, __ATOMIC_RELAXED, __HIP_MEMORY_SCOPE_AGENT); }
; __device__ __forceinline__ unsigned xb_add(unsigned* p, unsigned v) { return __hip_atomic_fetch_add(p, v, __ATOMIC_RELAXED, __HIP_MEMORY_SCOPE_AGENT); }
; #define XB_SPIN(cond, bar) do { unsigned _sp = 0; while (cond) { __builtin_amdgcn_s_sleep(1); \
;     if ((++_sp & 255u) == 0u) { if (xb_ld(&(bar)[XB_TMO])) break; if (_sp > XB_SPIN_CAP) { atomicAdd(&(bar)[XB_TMO], 1u); break; } } } } while (0)
; __device__ __forceinline__ void xcc_local_barrier(unsigned* bar2, unsigned x, unsigned nloc, unsigned* tmobar) {
;     asm volatile("s_waitcnt vmcnt(0)" ::: "memory");
;     __syncthreads();
;     if (threadIdx.x == 0) {
;         const unsigned old = xb_add(&bar2[XB_XSUB(x)], 1u);
;         const unsigned gen = old / nloc;
;         if (old + 1u == (gen + 1u) * nloc) (void)xb_add(&bar2[XB_XGEN(x)], 1u);
;         else XB_SPIN(xb_ld(&bar2[XB_XGEN(x)]) == gen, tmobar);
.LBB0_721:
	s_and_b64 vcc, exec, s[44:45]
	s_cbranch_vccz .LBB0_741
	v_readlane_b32 s6, v238, 25
	s_nop 1
	v_mov_b32_e32 v2, s6
	ds_read_b32 v2, v2
	s_waitcnt vmcnt(0)
	v_readlane_b32 s6, v242, 38
	v_readlane_b32 s7, v242, 39
	s_waitcnt vmcnt(0) lgkmcnt(0)
	s_barrier
	s_and_saveexec_b64 s[44:45], s[6:7]
	s_cbranch_execz .LBB0_740
	s_add_i32 s101, s101, 1
	v_readlane_b32 s6, v239, 63
	v_readlane_b32 s7, v241, 0
	v_readlane_b32 s98, v242, 4
	v_mov_b32_e32 v3, s101
	s_nop 3
	s_lshr_b32 s98, s98, 6
	s_lshl_b32 s98, s98, 2
	v_mov_b32_e32 v4, s98
	global_store_dword v4, v3, s[6:7] offset:128 sc1
	buffer_inv sc1
	s_mov_b32 s100, 0

; __device__ __forceinline__ unsigned xb_ld(unsigned* p)              { return __hip_atomic_load(p, __ATOMIC_RELAXED, __HIP_MEMORY_SCOPE_AGENT); }
; __device__ __forceinline__ unsigned xb_add(unsigned* p, unsigned v) { return __hip_atomic_fetch_add(p, v, __ATOMIC_RELAXED, __HIP_MEMORY_SCOPE_AGENT); }
; #define XB_SPIN(cond, bar) do { unsigned _sp = 0; while (cond) { __builtin_amdgcn_s_sleep(1); \
;     if ((++_sp & 255u) == 0u) { if (xb_ld(&(bar)[XB_TMO])) break; if (_sp > XB_SPIN_CAP) { atomicAdd(&(bar)[XB_TMO], 1u); break; } } } } while (0)
; __device__ __forceinline__ void xcc_local_barrier(unsigned* bar2, unsigned x, unsigned nloc, unsigned* tmobar) {
;     asm volatile("s_waitcnt vmcnt(0)" ::: "memory");
;     __syncthreads();
;     if (threadIdx.x == 0) {
;         const unsigned old = xb_add(&bar2[XB_XSUB(x)], 1u);
;         const unsigned gen = old / nloc;
;         if (old + 1u == (gen + 1u) * nloc) (void)xb_add(&bar2[XB_XGEN(x)], 1u);
;         else XB_SPIN(xb_ld(&bar2[XB_XGEN(x)]) == gen, tmobar);
.LBB0_1044:
	s_and_b64 vcc, exec, s[36:37]
	s_cbranch_vccz .LBB0_1064
	v_readlane_b32 s6, v238, 25
	s_nop 1
	v_mov_b32_e32 v2, s6
	ds_read_b32 v2, v2
	s_waitcnt vmcnt(0)
	v_readlane_b32 s6, v242, 38
	v_readlane_b32 s7, v242, 39
	s_waitcnt vmcnt(0) lgkmcnt(0)
	s_barrier
	s_and_saveexec_b64 s[36:37], s[6:7]
	s_cbranch_execz .LBB0_1063
	s_add_i32 s101, s101, 1
	v_readlane_b32 s6, v239, 63
	v_readlane_b32 s7, v241, 0
	v_readlane_b32 s98, v242, 4
	v_mov_b32_e32 v3, s101
	s_nop 3
	s_lshr_b32 s98, s98, 6
	s_lshl_b32 s98, s98, 2
	v_mov_b32_e32 v4, s98
	global_store_dword v4, v3, s[6:7] offset:128 sc1
	buffer_inv sc1
	s_mov_b32 s100, 0
